# stack12 + FFN hidden H kept block-permuted in d_ws (4x4 transpose of 16-byte pieces per 4-row x 64-byte block): FFN1 epilogue quads store whole 64-byte lines, FFN2 LDS-DMA source offsets and A-fragmen
# speedup vs baseline: 1.0124x; 1.0124x over previous
.LBB0_276:
	s_andn2_b64 vcc, exec, s[0:1]
	s_cbranch_vccnz .LBB0_316
	v_readlane_b32 s100, v248, 28
	v_and_b32_e32 v240, 63, v2
	v_lshrrev_b32_e32 v241, 4, v240
	v_bfe_u32 v242, v240, 2, 2
	v_sub_u32_e32 v243, 0, v241
	v_and_b32_e32 v243, 3, v243
	v_xor_b32_e32 v242, v242, v243
	v_lshl_or_b32 v241, v241, 2, v242
	v_lshrrev_b32_e32 v243, 7, v2
	v_lshl_or_b32 v241, v243, 4, v241
	v_and_b32_e32 v242, 3, v240
	v_lshlrev_b32_e32 v242, 3, v242
	s_cmp_eq_u32 s100, 7
	s_cselect_b64 s[100:101], -1, 0
	v_and_b32_e32 v240, 15, v2
	v_bfe_u32 v243, v2, 4, 2
	v_lshrrev_b32_e32 v244, 2, v240
	v_sub_u32_e32 v245, 0, v244
	v_and_b32_e32 v245, 3, v245
	v_xor_b32_e32 v243, v243, v245
	v_lshlrev_b32_e32 v244, 8, v244
	v_lshl_or_b32 v243, v243, 6, v244
	v_and_b32_e32 v240, 3, v240
	v_lshl_or_b32 v243, v240, 4, v243
	v_bfe_i32 v4, v2, 27, 1
	v_lshlrev_b32_e32 v3, 4, v2
	v_lshrrev_b32_e32 v4, 22, v4
	v_add_u32_e32 v4, v3, v4
	v_and_b32_e32 v4, 0xfffffc00, v4
	v_ashrrev_i32_e32 v0, 31, v2
	v_sub_u32_e32 v4, v3, v4
	v_lshrrev_b32_e32 v0, 26, v0
	v_lshrrev_b32_e32 v5, 4, v4
	v_add_u32_e32 v0, v2, v0
	v_bitop3_b32 v5, v5, v4, 32 bitop3:0x6c
	v_ashrrev_i32_e32 v4, 31, v4
	v_ashrrev_i32_e32 v0, 6, v0
	v_lshrrev_b32_e32 v4, 26, v4
	v_lshlrev_b32_e32 v6, 3, v0
	v_add_u32_e32 v4, v5, v4
	v_and_b32_e32 v6, -16, v6
	v_ashrrev_i32_e32 v4, 6, v4
	v_lshlrev_b32_e32 v0, 5, v0
	v_add_u32_e32 v6, v4, v6
	v_and_b32_e32 v169, 32, v0
	v_mul_i32_i24_e32 v0, 64, v4
	v_sub_u32_e32 v0, v5, v0
	v_lshlrev_b32_e32 v5, 1, v6
	v_lshrrev_b32_e32 v7, 2, v6
	v_and_b32_e32 v4, 3, v4
	s_mov_b32 s5, 0x7fffffe0
	v_ashrrev_i16_sdwa v0, v152, sext(v0) dst_sel:DWORD dst_unused:UNUSED_PAD src0_sel:DWORD src1_sel:BYTE_0
	v_and_b32_e32 v5, 24, v5
	v_and_b32_e32 v7, 4, v7
	v_and_or_b32 v4, v6, s5, v4
	v_bfe_i32 v170, v0, 0, 16
	v_or3_b32 v4, v4, v7, v5
	v_readlane_b32 s18, v248, 43
	v_add_u32_e32 v0, v169, v170
	v_add_u32_e32 v3, 0x2000, v3
	v_mul_lo_u32 v171, v6, s18
	v_mul_lo_u32 v4, v4, s18
	v_add_lshl_u32 v130, v0, v171, 1
	v_mul_lo_u32 v244, v241, s18
	v_add3_u32 v246, v244, v169, v242
	v_lshlrev_b32_e32 v246, 1, v246
	v_lshl_add_u32 v247, s18, 7, v246
	v_cndmask_b32_e64 v130, v130, v246, s[100:101]
	v_add_lshl_u32 v0, v4, v0, 1
	v_ashrrev_i32_e32 v4, 31, v3
	v_lshrrev_b32_e32 v4, 22, v4
	v_add_u32_e32 v4, v3, v4
	v_ashrrev_i32_e32 v4, 10, v4
	v_mul_i32_i24_e32 v5, 0x400, v4
	v_sub_u32_e32 v3, v3, v5
	v_lshrrev_b32_e32 v5, 4, v3
	v_bitop3_b32 v3, v5, v3, 32 bitop3:0x6c
	v_ashrrev_i32_e32 v6, 31, v3
	v_readlane_b32 s0, v248, 39
	v_lshrrev_b32_e32 v6, 26, v6
	v_readlane_b32 s1, v248, 40
	v_lshlrev_b32_e32 v5, 3, v4
	v_add_u32_e32 v6, v3, v6
	s_lshl_b64 s[0:1], s[0:1], 11
	v_readlane_b32 s6, v251, 7
	v_and_b32_e32 v5, -16, v5
	v_ashrrev_i32_e32 v7, 6, v6
	v_readlane_b32 s7, v251, 8
	s_add_u32 s10, s6, s0
	v_add_u32_e32 v5, v7, v5
	v_lshlrev_b32_e32 v4, 5, v4
	v_and_b32_e32 v7, 3, v7
	s_addc_u32 s11, s7, s1
	v_and_b32_e32 v172, 32, v4
	v_and_b32_e32 v4, 0xc0, v6
	v_and_or_b32 v7, v5, s5, v7
	s_ashr_i32 s5, s4, 8
	s_ashr_i32 s1, s4, 6
	v_sub_u32_e32 v3, v3, v4
	v_lshlrev_b32_e32 v4, 1, v5
	v_lshrrev_b32_e32 v6, 2, v5
	s_lshl_b32 s6, s5, 6
	s_lshl_b32 s7, s3, 8
	s_and_b32 s0, s1, 3
	v_ashrrev_i16_sdwa v3, v152, sext(v3) dst_sel:DWORD dst_unused:UNUSED_PAD src0_sel:DWORD src1_sel:BYTE_0
	v_and_b32_e32 v4, 24, v4
	v_and_b32_e32 v6, 4, v6
	v_and_b32_e32 v148, 15, v2
	s_add_i32 s7, s7, s6
	v_bfe_u32 v149, v2, 4, 2
	v_bfe_i32 v173, v3, 0, 16
	v_or3_b32 v4, v7, v6, v4
	s_lshl_b32 s23, s1, 10
	s_lshl_b32 s1, s0, 5
	v_or_b32_e32 v2, s7, v148
	s_lshl_b32 s7, s2, 8
	v_add_u32_e32 v3, v172, v173
	v_mul_lo_u32 v174, v5, s18
	v_mul_lo_u32 v4, v4, s18
	v_lshlrev_b32_e32 v168, 3, v149
	s_or_b32 s7, s7, s1
	v_or_b32_e32 v8, 16, v2
	v_add_lshl_u32 v132, v3, v174, 1
	v_cndmask_b32_e64 v132, v132, v247, s[100:101]
	v_add_lshl_u32 v134, v4, v3, 1
	v_or_b32_e32 v4, s7, v168
	v_ashrrev_i32_e32 v3, 31, v2
	v_ashrrev_i32_e32 v9, 31, v8
	v_ashrrev_i32_e32 v5, 31, v4
	v_lshlrev_b64 v[6:7], 11, v[2:3]
	v_lshlrev_b64 v[8:9], 11, v[8:9]
	v_lshl_add_u64 v[6:7], s[10:11], 0, v[6:7]
	v_lshlrev_b64 v[4:5], 1, v[4:5]
	v_lshl_add_u64 v[8:9], s[10:11], 0, v[8:9]
	v_lshl_add_u64 v[6:7], v[6:7], 0, v[4:5]
	v_lshl_add_u64 v[8:9], v[8:9], 0, v[4:5]
	global_load_dwordx4 v[62:65], v[6:7], off
	global_load_dwordx4 v[54:57], v[6:7], off offset:256
	global_load_dwordx4 v[58:61], v[8:9], off
	global_load_dwordx4 v[46:49], v[8:9], off offset:256
	v_or_b32_e32 v8, 32, v2
	v_or_b32_e32 v2, 48, v2
	v_ashrrev_i32_e32 v9, 31, v8
	v_ashrrev_i32_e32 v3, 31, v2
	v_lshlrev_b64 v[8:9], 11, v[8:9]
	v_lshlrev_b64 v[2:3], 11, v[2:3]
	v_lshl_add_u64 v[8:9], s[10:11], 0, v[8:9]
	v_lshl_add_u64 v[2:3], s[10:11], 0, v[2:3]
	s_mov_b32 s7, 0x40000
	v_lshl_add_u64 v[8:9], v[8:9], 0, v[4:5]
	v_lshl_add_u64 v[2:3], v[2:3], 0, v[4:5]
	v_add_co_u32_e32 v4, vcc, s7, v6
	s_mov_b64 s[90:91], 0x40000
	s_nop 0
	v_addc_co_u32_e32 v5, vcc, 0, v7, vcc
	s_mov_b32 s7, 0x48000
	global_load_dwordx4 v[50:53], v[8:9], off
	global_load_dwordx4 v[38:41], v[8:9], off offset:256
	global_load_dwordx4 v[42:45], v[2:3], off
	global_load_dwordx4 v[30:33], v[2:3], off offset:256
	v_lshl_add_u64 v[2:3], v[6:7], 0, s[90:91]
	global_load_dwordx4 v[34:37], v[4:5], off
	global_load_dwordx4 v[18:21], v[2:3], off offset:256
	v_add_co_u32_e32 v4, vcc, s7, v6
	s_mov_b64 s[92:93], 0x48000
	s_nop 0
	v_addc_co_u32_e32 v5, vcc, 0, v7, vcc
	s_mov_b32 s7, 0x50000
	v_lshl_add_u64 v[2:3], v[6:7], 0, s[92:93]
	global_load_dwordx4 v[26:29], v[4:5], off
	global_load_dwordx4 v[10:13], v[2:3], off offset:256
	v_add_co_u32_e32 v4, vcc, s7, v6
	s_lshl_b32 s80, s18, 8
	s_mov_b64 s[98:99], 0x50000
	v_addc_co_u32_e32 v5, vcc, 0, v7, vcc
	s_mov_b64 s[8:9], 0x58000
	s_mov_b32 s7, 0x58000
	s_lshl_b64 s[14:15], s[80:81], 1
	v_lshl_add_u64 v[2:3], v[6:7], 0, s[98:99]
	v_lshl_add_u64 v[22:23], v[6:7], 0, s[8:9]
	v_add_co_u32_e32 v6, vcc, s7, v6
	s_ashr_i32 s7, s3, 31
	s_mul_i32 s7, s14, s7
	s_mul_hi_u32 s8, s14, s3
	s_add_i32 s7, s8, s7
	s_bfe_u32 s8, s18, 0x10017
	s_mul_i32 s9, s8, s3
	s_add_i32 s7, s7, s9
	s_ashr_i32 s9, s2, 31
	s_mul_i32 s9, s14, s9
	s_mul_hi_u32 s16, s14, s2
	s_add_i32 s9, s16, s9
	s_mul_i32 s8, s8, s2
	s_add_i32 s9, s9, s8
	s_mul_i32 s8, s14, s2
	v_readlane_b32 s16, v248, 46
	v_readlane_b32 s17, v248, 47
	s_add_u32 s54, s16, s8
	s_addc_u32 s55, s17, s9
	s_add_i32 s58, s23, 0
	v_addc_co_u32_e32 v7, vcc, 0, v7, vcc
	s_add_i32 m0, s58, 0x10000
	s_waitcnt lgkmcnt(0)
	global_load_dwordx4 v[14:17], v[4:5], off
	s_nop 0
	global_load_dwordx4 v[2:5], v[2:3], off offset:256
	s_nop 0
	global_load_dwordx4 v[6:9], v[6:7], off
	s_nop 0
	global_load_dwordx4 v[22:25], v[22:23], off offset:256
	v_mov_b32_e32 v135, v1
	global_load_lds_dwordx4 v0, s[54:55]
	s_add_i32 m0, s58, 0x12000
	s_add_u32 s8, s54, s80
	global_load_lds_dwordx4 v134, s[54:55]
	s_addc_u32 s9, s55, 0
	s_add_i32 m0, s58, 0x14000
	s_mul_i32 s13, s14, s3
	global_load_lds_dwordx4 v0, s[8:9]
	s_add_i32 m0, s58, 0x16000
	v_lshl_add_u64 v[140:141], s[8:9], 0, v[0:1]
	v_lshl_add_u64 v[142:143], s[8:9], 0, v[134:135]
	global_load_lds_dwordx4 v134, s[8:9]
	v_readlane_b32 s8, v248, 48
	v_readlane_b32 s9, v248, 49
	s_add_u32 s56, s8, s13
	s_addc_u32 s57, s9, s7
	s_add_i32 s59, s58, 0x2000
	s_mov_b32 m0, s58
	s_add_u32 s8, s56, s80
	global_load_lds_dwordx4 v130, s[56:57]
	s_mov_b32 m0, s59
	s_addc_u32 s9, s57, 0
	s_add_i32 s60, s58, 0x4000
	global_load_lds_dwordx4 v132, s[56:57]
	s_mov_b32 m0, s60
	s_add_i32 s61, s58, 0x6000
	global_load_lds_dwordx4 v130, s[8:9]
	s_mov_b32 m0, s61
	s_cmp_eq_u32 s5, 1
	global_load_lds_dwordx4 v132, s[8:9]
	v_mov_b32_e32 v131, v1
	v_mov_b32_e32 v133, v1
	s_cselect_b64 s[8:9], -1, 0
	v_lshl_add_u64 v[136:137], s[54:55], 0, v[0:1]
	v_lshl_add_u64 v[138:139], s[54:55], 0, v[134:135]
	v_lshl_add_u64 v[144:145], s[56:57], 0, v[130:131]
	v_lshl_add_u64 v[146:147], s[56:57], 0, v[132:133]
	v_writelane_b32 v248, s8, 29
	s_cmp_lg_u32 s5, 1
	s_nop 0
	v_writelane_b32 v248, s9, 30
	s_cbranch_scc1 .LBB0_279
	s_barrier
.LBB0_279:
	v_readlane_b32 s8, v248, 39
	v_readlane_b32 s9, v248, 40
	s_lshl_b64 s[8:9], s[8:9], 4
	v_readlane_b32 s16, v248, 54
	v_readlane_b32 s17, v248, 55
	s_add_u32 s62, s16, s8
	s_waitcnt vmcnt(0)
	v_lshlrev_b32_e32 v126, 16, v62
	v_and_b32_e32 v127, 0xffff0000, v62
	v_lshlrev_b32_e32 v128, 16, v63
	v_and_b32_e32 v129, 0xffff0000, v63
	v_lshlrev_b32_e32 v114, 16, v64
	v_and_b32_e32 v115, 0xffff0000, v64
	v_lshlrev_b32_e32 v116, 16, v65
	v_and_b32_e32 v117, 0xffff0000, v65
	v_lshlrev_b32_e32 v106, 16, v58
	v_and_b32_e32 v107, 0xffff0000, v58
	v_lshlrev_b32_e32 v108, 16, v59
	v_and_b32_e32 v109, 0xffff0000, v59
	v_lshlrev_b32_e32 v98, 16, v60
	v_and_b32_e32 v99, 0xffff0000, v60
	v_lshlrev_b32_e32 v100, 16, v61
	v_and_b32_e32 v101, 0xffff0000, v61
	v_lshlrev_b32_e32 v58, 16, v34
	v_and_b32_e32 v59, 0xffff0000, v34
	v_lshlrev_b32_e32 v60, 16, v35
	v_and_b32_e32 v61, 0xffff0000, v35
	v_lshlrev_b32_e32 v62, 16, v36
	v_and_b32_e32 v63, 0xffff0000, v36
	v_lshlrev_b32_e32 v64, 16, v37
	v_and_b32_e32 v65, 0xffff0000, v37
	v_lshlrev_b32_e32 v34, 16, v10
	v_and_b32_e32 v35, 0xffff0000, v10
	v_lshlrev_b32_e32 v36, 16, v11
	v_and_b32_e32 v37, 0xffff0000, v11
	s_addc_u32 s63, s17, s9
	s_add_i32 m0, s58, 0x18000
	v_lshl_add_u64 v[10:11], v[136:137], 0, s[94:95]
	s_waitcnt vmcnt(2)
	s_barrier
	global_load_lds_dwordx4 v[10:11], off
	v_lshl_add_u64 v[10:11], v[138:139], 0, s[94:95]
	s_add_i32 m0, s58, 0x1a000
	s_add_i32 s64, s58, 0x8000
	global_load_lds_dwordx4 v[10:11], off
	v_lshl_add_u64 v[10:11], v[144:145], 0, s[94:95]
	s_mov_b32 m0, s64
	s_add_i32 s65, s58, 0xa000
	global_load_lds_dwordx4 v[10:11], off
	v_lshl_add_u64 v[10:11], v[146:147], 0, s[94:95]
	s_mov_b32 m0, s65
	v_or_b32_e32 v146, s6, v148
	global_load_lds_dwordx4 v[10:11], off
	s_add_i32 m0, s58, 0x1c000
	v_lshl_add_u64 v[10:11], v[140:141], 0, s[94:95]
	global_load_lds_dwordx4 v[10:11], off
	v_lshl_add_u64 v[10:11], v[142:143], 0, s[94:95]
	s_add_i32 m0, s58, 0x1e000
	v_lshlrev_b32_e32 v136, 6, v146
	global_load_lds_dwordx4 v[10:11], off
	v_lshlrev_b32_e32 v137, 4, v149
	s_movk_i32 s6, 0x3c0
	v_lshlrev_b32_e32 v138, 2, v146
	s_lshr_b32 s66, s18, 6
	v_and_or_b32 v136, v136, s6, v137
	s_lshl_b32 s5, s5, 13
	v_and_b32_e32 v138, 32, v138
	v_bitop3_b32 v140, v136, s5, v138 bitop3:0xde
	v_lshl_or_b32 v136, v148, 6, v137
	s_lshl_b32 s5, s0, 12
	v_lshlrev_b32_e32 v137, 2, v148
	s_add_i32 s67, s66, -2
	v_and_b32_e32 v137, 32, v137
	s_cmpk_lt_u32 s4, 0x100
	v_readlane_b32 s8, v248, 42
	v_bitop3_b32 v147, v136, s5, v137 bitop3:0xde
	s_cselect_b64 s[20:21], -1, 0
	v_or_b32_e32 v136, s0, v149
	s_lshl_b32 s71, s8, 2
	v_cmp_eq_u32_e64 s[6:7], 0, v136
	v_cvt_f32_u32_e32 v136, s71
	v_add_u32_e32 v148, 0x80, v146
	v_readlane_b32 s8, v249, 45
	s_lshl_b32 s0, s0, 2
	v_rcp_iflag_f32_e32 v136, v136
	v_lshl_add_u32 v164, v146, 4, s8
	v_lshl_add_u32 v166, v148, 4, s8
	v_add_u32_e32 v165, s0, v164
	v_mul_f32_e32 v136, 0x4f7ffffe, v136
	v_cvt_u32_f32_e32 v136, v136
	v_add_u32_e32 v167, s0, v166
	v_or_b32_e32 v168, s1, v168
	s_sub_i32 s0, 0, s71
	v_readfirstlane_b32 s1, v136
	s_waitcnt vmcnt(6)
	v_cmp_eq_u32_e64 s[4:5], 0, v149
	v_or_b32_e32 v149, 16, v146
	v_or_b32_e32 v159, 32, v146
	v_or_b32_e32 v160, 48, v146
	v_add_u32_e32 v161, 0x90, v146
	v_add_u32_e32 v162, 0xa0, v146
	v_add_u32_e32 v163, 0xb0, v146
	s_mul_i32 s0, s0, s1
	v_add_u32_e32 v136, v171, v169
	v_add_u32_e32 v138, v174, v172
	v_lshlrev_b32_e32 v141, 4, v149
	v_lshlrev_b32_e32 v142, 4, v159
	v_lshlrev_b32_e32 v143, 4, v160
	v_lshlrev_b32_e32 v144, 4, v161
	v_lshlrev_b32_e32 v145, 4, v162
	v_lshlrev_b32_e32 v175, 4, v163
	s_mul_hi_u32 s0, s1, s0
	v_add_lshl_u32 v136, v136, v170, 1
	v_cndmask_b32_e64 v136, v136, v246, s[100:101]
	v_mov_b32_e32 v137, v1
	v_add_lshl_u32 v138, v138, v173, 1
	v_cndmask_b32_e64 v138, v138, v247, s[100:101]
	v_mov_b32_e32 v139, v1
	v_lshlrev_b32_e32 v118, 16, v54
	v_and_b32_e32 v119, 0xffff0000, v54
	v_lshlrev_b32_e32 v120, 16, v55
	v_and_b32_e32 v121, 0xffff0000, v55
	v_lshlrev_b32_e32 v122, 16, v56
	v_and_b32_e32 v123, 0xffff0000, v56
	v_lshlrev_b32_e32 v124, 16, v57
	v_and_b32_e32 v125, 0xffff0000, v57
	v_lshlrev_b32_e32 v102, 16, v46
	v_and_b32_e32 v103, 0xffff0000, v46
	v_lshlrev_b32_e32 v104, 16, v47
	v_and_b32_e32 v105, 0xffff0000, v47
	v_lshlrev_b32_e32 v110, 16, v48
	v_and_b32_e32 v111, 0xffff0000, v48
	v_lshlrev_b32_e32 v112, 16, v49
	v_and_b32_e32 v113, 0xffff0000, v49
	v_lshlrev_b32_e32 v90, 16, v50
	v_and_b32_e32 v91, 0xffff0000, v50
	v_lshlrev_b32_e32 v92, 16, v51
	v_and_b32_e32 v93, 0xffff0000, v51
	v_lshlrev_b32_e32 v82, 16, v52
	v_and_b32_e32 v83, 0xffff0000, v52
	v_lshlrev_b32_e32 v84, 16, v53
	v_and_b32_e32 v85, 0xffff0000, v53
	v_lshlrev_b32_e32 v86, 16, v38
	v_and_b32_e32 v87, 0xffff0000, v38
	v_lshlrev_b32_e32 v88, 16, v39
	v_and_b32_e32 v89, 0xffff0000, v39
	v_lshlrev_b32_e32 v94, 16, v40
	v_and_b32_e32 v95, 0xffff0000, v40
	v_lshlrev_b32_e32 v96, 16, v41
	v_and_b32_e32 v97, 0xffff0000, v41
	v_lshlrev_b32_e32 v74, 16, v42
	v_and_b32_e32 v75, 0xffff0000, v42
	v_lshlrev_b32_e32 v76, 16, v43
	v_and_b32_e32 v77, 0xffff0000, v43
	v_lshlrev_b32_e32 v54, 16, v44
	v_and_b32_e32 v55, 0xffff0000, v44
	v_lshlrev_b32_e32 v56, 16, v45
	v_and_b32_e32 v57, 0xffff0000, v45
	v_lshlrev_b32_e32 v70, 16, v30
	v_and_b32_e32 v71, 0xffff0000, v30
	v_lshlrev_b32_e32 v72, 16, v31
	v_and_b32_e32 v73, 0xffff0000, v31
	v_lshlrev_b32_e32 v78, 16, v32
	v_and_b32_e32 v79, 0xffff0000, v32
	v_lshlrev_b32_e32 v80, 16, v33
	v_and_b32_e32 v81, 0xffff0000, v33
	v_lshlrev_b32_e32 v50, 16, v18
	v_and_b32_e32 v51, 0xffff0000, v18
	v_lshlrev_b32_e32 v52, 16, v19
	v_and_b32_e32 v53, 0xffff0000, v19
	v_lshlrev_b32_e32 v66, 16, v20
	v_and_b32_e32 v67, 0xffff0000, v20
	v_lshlrev_b32_e32 v68, 16, v21
	v_and_b32_e32 v69, 0xffff0000, v21
	v_lshlrev_b32_e32 v38, 16, v26
	v_and_b32_e32 v39, 0xffff0000, v26
	v_lshlrev_b32_e32 v40, 16, v27
	v_and_b32_e32 v41, 0xffff0000, v27
	v_lshlrev_b32_e32 v42, 16, v28
	v_and_b32_e32 v43, 0xffff0000, v28
	v_lshlrev_b32_e32 v44, 16, v29
	v_and_b32_e32 v45, 0xffff0000, v29
	v_lshlrev_b32_e32 v46, 16, v12
	v_and_b32_e32 v47, 0xffff0000, v12
	v_lshlrev_b32_e32 v48, 16, v13
	v_and_b32_e32 v49, 0xffff0000, v13
	v_lshlrev_b32_e32 v18, 16, v14
	v_and_b32_e32 v19, 0xffff0000, v14
	v_lshlrev_b32_e32 v20, 16, v15
	v_and_b32_e32 v21, 0xffff0000, v15
	v_lshlrev_b32_e32 v26, 16, v16
	v_and_b32_e32 v27, 0xffff0000, v16
	v_lshlrev_b32_e32 v28, 16, v17
	v_and_b32_e32 v29, 0xffff0000, v17
	v_lshlrev_b32_e32 v14, 16, v2
	v_and_b32_e32 v15, 0xffff0000, v2
	v_lshlrev_b32_e32 v16, 16, v3
	v_and_b32_e32 v17, 0xffff0000, v3
	v_lshlrev_b32_e32 v30, 16, v4
	v_and_b32_e32 v31, 0xffff0000, v4
	v_lshlrev_b32_e32 v32, 16, v5
	v_and_b32_e32 v33, 0xffff0000, v5
	v_lshlrev_b32_e32 v2, 16, v6
	v_and_b32_e32 v3, 0xffff0000, v6
	v_lshlrev_b32_e32 v4, 16, v7
	v_and_b32_e32 v5, 0xffff0000, v7
	v_lshlrev_b32_e32 v6, 16, v8
	v_and_b32_e32 v7, 0xffff0000, v8
	v_lshlrev_b32_e32 v8, 16, v9
	v_and_b32_e32 v9, 0xffff0000, v9
	v_lshlrev_b32_e32 v10, 16, v22
	v_and_b32_e32 v11, 0xffff0000, v22
	v_lshlrev_b32_e32 v12, 16, v23
	v_and_b32_e32 v13, 0xffff0000, v23
	v_lshlrev_b32_e32 v22, 16, v24
	v_and_b32_e32 v23, 0xffff0000, v24
	v_lshlrev_b32_e32 v24, 16, v25
	v_and_b32_e32 v25, 0xffff0000, v25
	s_mov_b32 s70, 0
	s_mov_b32 s13, s81
	s_lshr_b32 s96, s12, 3
	s_add_i32 s97, s1, s0
	v_lshl_add_u64 v[136:137], s[80:81], 0, v[136:137]
	v_lshl_add_u64 v[138:139], s[80:81], 0, v[138:139]
	v_add_u32_e32 v169, 0, v140
	v_lshrrev_b32_e32 v245, 10, v169
	v_lshl_or_b32 v245, v245, 10, v243
	v_cndmask_b32_e64 v169, v169, v245, s[100:101]
	v_add_u32_e32 v170, s8, v141
	v_add_u32_e32 v171, s8, v142
	v_add_u32_e32 v172, s8, v143
	v_add_u32_e32 v173, s8, v144
	v_add_u32_e32 v174, s8, v145
	v_add_u32_e32 v175, s8, v175
	s_barrier
	s_branch .LBB0_282

.LBB0_337:
	v_and_b32_e32 v234, 15, v150
	v_bfe_u32 v235, v150, 4, 2
	v_lshrrev_b32_e32 v236, 2, v234
	v_and_b32_e32 v234, 3, v234
	v_lshl_or_b32 v235, v236, 2, v235
	v_lshlrev_b32_e32 v234, 3, v234
	v_and_or_b32 v232, v142, -16, v235
	v_lshrrev_b32_e32 v233, 5, v144
	v_lshl_or_b32 v233, v233, 5, v234
	ds_read_b128 v[160:163], v147
	v_lshl_add_u32 v148, s62, 8, v232
	v_ashrrev_i32_e32 v149, 31, v148
	v_mul_lo_u32 v149, s68, v149
	v_mul_lo_u32 v159, s69, v148
	s_waitcnt lgkmcnt(0)
	v_mov_b32_e32 v166, v161
	v_mov_b32_e32 v167, v162
	v_mov_b32_e32 v161, v163
	v_mad_u64_u32 v[164:165], s[16:17], s68, v148, 0
	v_pk_add_f32 v[160:161], v[166:167], v[160:161]
	v_add3_u32 v165, v165, v149, v159
	v_add_f32_e32 v159, v160, v161
	v_fmamk_f32 v159, v159, 0x3a800000, v155
	v_rsq_f32_e32 v159, v159
	v_lshl_add_u64 v[160:161], v[164:165], 1, s[78:79]
	v_lshl_or_b32 v140, s63, 8, v233
	v_ashrrev_i32_e32 v141, 31, v140
	v_mul_f32_e32 v162, v159, v159
	v_max_f32_e32 v165, 0, v129
	v_max_f32_e32 v164, 0, v128
	v_max_f32_e32 v167, 0, v127
	v_max_f32_e32 v166, 0, v126
	v_pk_mul_f32 v[128:129], v[128:129], v[164:165]
	v_max_f32_e32 v165, 0, v125
	v_max_f32_e32 v164, 0, v124
	v_pk_mul_f32 v[126:127], v[126:127], v[166:167]
	v_max_f32_e32 v167, 0, v123
	v_max_f32_e32 v166, 0, v122
	v_pk_mul_f32 v[122:123], v[122:123], v[166:167]
	v_pk_mul_f32 v[124:125], v[124:125], v[164:165]
	v_lshlrev_b64 v[140:141], 1, v[140:141]
	v_pk_mul_f32 v[164:165], v[124:125], v[162:163] op_sel_hi:[1,0]
	v_pk_mul_f32 v[124:125], v[122:123], v[162:163] op_sel_hi:[1,0]
	v_lshl_add_u64 v[160:161], v[160:161], 0, v[140:141]
	v_pk_mul_f32 v[128:129], v[128:129], v[162:163] op_sel_hi:[1,0]
	v_pk_mul_f32 v[126:127], v[126:127], v[162:163] op_sel_hi:[1,0]
	s_and_b64 vcc, exec, s[6:7]
	v_cvt_pk_bf16_f32 v122, v126, v127
	v_cvt_pk_bf16_f32 v123, v128, v129
	v_cvt_pk_bf16_f32 v124, v124, v125
	v_cvt_pk_bf16_f32 v125, v164, v165
	global_store_dwordx4 v[160:161], v[122:125], off
	s_mov_b64 s[6:7], -1
	s_nop 0
	v_max_f32_e32 v123, 0, v121
	v_max_f32_e32 v125, 0, v119
	v_max_f32_e32 v122, 0, v120
	v_max_f32_e32 v124, 0, v118
	v_pk_mul_f32 v[118:119], v[118:119], v[124:125]
	v_pk_mul_f32 v[120:121], v[120:121], v[122:123]
	v_max_f32_e32 v123, 0, v117
	v_max_f32_e32 v125, 0, v115
	v_max_f32_e32 v122, 0, v116
	v_max_f32_e32 v124, 0, v114
	v_pk_mul_f32 v[114:115], v[114:115], v[124:125]
	v_pk_mul_f32 v[116:117], v[116:117], v[122:123]
	v_pk_mul_f32 v[120:121], v[120:121], v[162:163] op_sel_hi:[1,0]
	v_pk_mul_f32 v[122:123], v[116:117], v[162:163] op_sel_hi:[1,0]
	v_pk_mul_f32 v[116:117], v[114:115], v[162:163] op_sel_hi:[1,0]
	v_pk_mul_f32 v[118:119], v[118:119], v[162:163] op_sel_hi:[1,0]
	s_nop 0
	v_cvt_pk_bf16_f32 v114, v118, v119
	v_cvt_pk_bf16_f32 v115, v120, v121
	v_cvt_pk_bf16_f32 v116, v116, v117
	v_cvt_pk_bf16_f32 v117, v122, v123
	global_store_dwordx4 v[160:161], v[114:117], off offset:256
	ds_read_b128 v[114:117], v147 offset:256
	v_or_b32_e32 v118, 16, v148
	v_mul_lo_u32 v122, s69, v118
	v_mad_u64_u32 v[118:119], s[16:17], s68, v118, 0
	s_waitcnt lgkmcnt(0)
	v_mov_b32_e32 v120, v115
	v_mov_b32_e32 v121, v116
	v_mov_b32_e32 v115, v117
	v_pk_add_f32 v[114:115], v[120:121], v[114:115]
	v_add3_u32 v119, v119, v149, v122
	v_add_f32_e32 v114, v114, v115
	v_fmamk_f32 v114, v114, 0x3a800000, v155
	v_rsq_f32_e32 v116, v114
	v_lshl_add_u64 v[114:115], v[118:119], 1, s[78:79]
	v_max_f32_e32 v119, 0, v113
	v_max_f32_e32 v118, 0, v112
	v_max_f32_e32 v121, 0, v111
	v_max_f32_e32 v120, 0, v110
	v_mul_f32_e32 v116, v116, v116
	v_pk_mul_f32 v[110:111], v[110:111], v[120:121]
	v_pk_mul_f32 v[112:113], v[112:113], v[118:119]
	v_pk_mul_f32 v[110:111], v[110:111], v[116:117] op_sel_hi:[1,0]
	v_pk_mul_f32 v[112:113], v[112:113], v[116:117] op_sel_hi:[1,0]
	v_max_f32_e32 v119, 0, v109
	v_max_f32_e32 v118, 0, v108
	v_max_f32_e32 v121, 0, v107
	v_max_f32_e32 v120, 0, v106
	v_pk_mul_f32 v[106:107], v[106:107], v[120:121]
	v_pk_mul_f32 v[108:109], v[108:109], v[118:119]
	v_lshl_add_u64 v[114:115], v[114:115], 0, v[140:141]
	v_pk_mul_f32 v[118:119], v[108:109], v[116:117] op_sel_hi:[1,0]
	v_pk_mul_f32 v[108:109], v[106:107], v[116:117] op_sel_hi:[1,0]
	v_cvt_pk_bf16_f32 v106, v110, v111
	v_cvt_pk_bf16_f32 v107, v112, v113
	s_nop 0
	v_cvt_pk_bf16_f32 v108, v108, v109
	v_cvt_pk_bf16_f32 v109, v118, v119
	global_store_dwordx4 v[114:115], v[106:109], off
	s_nop 1
	v_max_f32_e32 v107, 0, v105
	v_max_f32_e32 v109, 0, v103
	v_max_f32_e32 v106, 0, v104
	v_max_f32_e32 v108, 0, v102
	v_pk_mul_f32 v[102:103], v[102:103], v[108:109]
	v_pk_mul_f32 v[104:105], v[104:105], v[106:107]
	v_max_f32_e32 v107, 0, v101
	v_max_f32_e32 v109, 0, v99
	v_max_f32_e32 v106, 0, v100
	v_max_f32_e32 v108, 0, v98
	v_pk_mul_f32 v[98:99], v[98:99], v[108:109]
	v_pk_mul_f32 v[100:101], v[100:101], v[106:107]
	v_pk_mul_f32 v[104:105], v[104:105], v[116:117] op_sel_hi:[1,0]
	v_pk_mul_f32 v[106:107], v[100:101], v[116:117] op_sel_hi:[1,0]
	v_pk_mul_f32 v[100:101], v[98:99], v[116:117] op_sel_hi:[1,0]
	v_pk_mul_f32 v[102:103], v[102:103], v[116:117] op_sel_hi:[1,0]
	s_nop 0
	v_cvt_pk_bf16_f32 v98, v102, v103
	v_cvt_pk_bf16_f32 v99, v104, v105
	v_cvt_pk_bf16_f32 v100, v100, v101
	v_cvt_pk_bf16_f32 v101, v106, v107
	global_store_dwordx4 v[114:115], v[98:101], off offset:256
	ds_read_b128 v[98:101], v147 offset:512
	v_or_b32_e32 v102, 32, v148
	v_mul_lo_u32 v106, s69, v102
	v_mad_u64_u32 v[102:103], s[16:17], s68, v102, 0
	s_waitcnt lgkmcnt(0)
	v_mov_b32_e32 v104, v99
	v_mov_b32_e32 v105, v100
	v_mov_b32_e32 v99, v101
	v_pk_add_f32 v[98:99], v[104:105], v[98:99]
	v_add3_u32 v103, v103, v149, v106
	v_add_f32_e32 v98, v98, v99
	v_fmamk_f32 v98, v98, 0x3a800000, v155
	v_rsq_f32_e32 v100, v98
	v_lshl_add_u64 v[98:99], v[102:103], 1, s[78:79]
	v_max_f32_e32 v103, 0, v97
	v_max_f32_e32 v102, 0, v96
	v_max_f32_e32 v105, 0, v95
	v_max_f32_e32 v104, 0, v94
	v_mul_f32_e32 v100, v100, v100
	v_pk_mul_f32 v[94:95], v[94:95], v[104:105]
	v_pk_mul_f32 v[96:97], v[96:97], v[102:103]
	v_pk_mul_f32 v[94:95], v[94:95], v[100:101] op_sel_hi:[1,0]
	v_pk_mul_f32 v[96:97], v[96:97], v[100:101] op_sel_hi:[1,0]
	v_max_f32_e32 v103, 0, v93
	v_max_f32_e32 v102, 0, v92
	v_max_f32_e32 v105, 0, v91
	v_max_f32_e32 v104, 0, v90
	v_pk_mul_f32 v[90:91], v[90:91], v[104:105]
	v_pk_mul_f32 v[92:93], v[92:93], v[102:103]
	v_lshl_add_u64 v[98:99], v[98:99], 0, v[140:141]
	v_pk_mul_f32 v[102:103], v[92:93], v[100:101] op_sel_hi:[1,0]
	v_pk_mul_f32 v[92:93], v[90:91], v[100:101] op_sel_hi:[1,0]
	v_cvt_pk_bf16_f32 v90, v94, v95
	v_cvt_pk_bf16_f32 v91, v96, v97
	s_nop 0
	v_cvt_pk_bf16_f32 v92, v92, v93
	v_cvt_pk_bf16_f32 v93, v102, v103
	global_store_dwordx4 v[98:99], v[90:93], off
	s_nop 1
	v_max_f32_e32 v91, 0, v89
	v_max_f32_e32 v93, 0, v87
	v_max_f32_e32 v90, 0, v88
	v_max_f32_e32 v92, 0, v86
	v_pk_mul_f32 v[86:87], v[86:87], v[92:93]
	v_pk_mul_f32 v[88:89], v[88:89], v[90:91]
	v_max_f32_e32 v91, 0, v85
	v_max_f32_e32 v93, 0, v83
	v_max_f32_e32 v90, 0, v84
	v_max_f32_e32 v92, 0, v82
	v_pk_mul_f32 v[82:83], v[82:83], v[92:93]
	v_pk_mul_f32 v[84:85], v[84:85], v[90:91]
	v_pk_mul_f32 v[88:89], v[88:89], v[100:101] op_sel_hi:[1,0]
	v_pk_mul_f32 v[90:91], v[84:85], v[100:101] op_sel_hi:[1,0]
	v_pk_mul_f32 v[84:85], v[82:83], v[100:101] op_sel_hi:[1,0]
	v_pk_mul_f32 v[86:87], v[86:87], v[100:101] op_sel_hi:[1,0]
	s_nop 0
	v_cvt_pk_bf16_f32 v82, v86, v87
	v_cvt_pk_bf16_f32 v83, v88, v89
	v_cvt_pk_bf16_f32 v84, v84, v85
	v_cvt_pk_bf16_f32 v85, v90, v91
	global_store_dwordx4 v[98:99], v[82:85], off offset:256
	ds_read_b128 v[82:85], v147 offset:768
	v_or_b32_e32 v86, 48, v148
	v_mul_lo_u32 v90, s69, v86
	v_mad_u64_u32 v[86:87], s[16:17], s68, v86, 0
	s_waitcnt lgkmcnt(0)
	v_mov_b32_e32 v88, v83
	v_mov_b32_e32 v89, v84
	v_mov_b32_e32 v83, v85
	v_pk_add_f32 v[82:83], v[88:89], v[82:83]
	v_add3_u32 v87, v87, v149, v90
	v_add_f32_e32 v82, v82, v83
	v_fmamk_f32 v82, v82, 0x3a800000, v155
	v_rsq_f32_e32 v84, v82
	v_lshl_add_u64 v[82:83], v[86:87], 1, s[78:79]
	v_max_f32_e32 v87, 0, v81
	v_max_f32_e32 v86, 0, v80
	v_max_f32_e32 v89, 0, v79
	v_max_f32_e32 v88, 0, v78
	v_mul_f32_e32 v84, v84, v84
	v_pk_mul_f32 v[78:79], v[78:79], v[88:89]
	v_pk_mul_f32 v[80:81], v[80:81], v[86:87]
	v_pk_mul_f32 v[78:79], v[78:79], v[84:85] op_sel_hi:[1,0]
	v_pk_mul_f32 v[80:81], v[80:81], v[84:85] op_sel_hi:[1,0]
	v_max_f32_e32 v87, 0, v77
	v_max_f32_e32 v86, 0, v76
	v_max_f32_e32 v89, 0, v75
	v_max_f32_e32 v88, 0, v74
	v_pk_mul_f32 v[74:75], v[74:75], v[88:89]
	v_pk_mul_f32 v[76:77], v[76:77], v[86:87]
	v_lshl_add_u64 v[82:83], v[82:83], 0, v[140:141]
	v_pk_mul_f32 v[86:87], v[76:77], v[84:85] op_sel_hi:[1,0]
	v_pk_mul_f32 v[76:77], v[74:75], v[84:85] op_sel_hi:[1,0]
	v_cvt_pk_bf16_f32 v74, v78, v79
	v_cvt_pk_bf16_f32 v75, v80, v81
	s_nop 0
	v_cvt_pk_bf16_f32 v76, v76, v77
	v_cvt_pk_bf16_f32 v77, v86, v87
	global_store_dwordx4 v[82:83], v[74:77], off
	s_nop 1
	v_max_f32_e32 v75, 0, v73
	v_max_f32_e32 v77, 0, v71
	v_max_f32_e32 v74, 0, v72
	v_max_f32_e32 v76, 0, v70
	v_pk_mul_f32 v[70:71], v[70:71], v[76:77]
	v_pk_mul_f32 v[72:73], v[72:73], v[74:75]
	v_max_f32_e32 v75, 0, v69
	v_max_f32_e32 v77, 0, v67
	v_max_f32_e32 v74, 0, v68
	v_max_f32_e32 v76, 0, v66
	v_pk_mul_f32 v[66:67], v[66:67], v[76:77]
	v_pk_mul_f32 v[68:69], v[68:69], v[74:75]
	v_pk_mul_f32 v[72:73], v[72:73], v[84:85] op_sel_hi:[1,0]
	v_pk_mul_f32 v[74:75], v[68:69], v[84:85] op_sel_hi:[1,0]
	v_pk_mul_f32 v[68:69], v[66:67], v[84:85] op_sel_hi:[1,0]
	v_pk_mul_f32 v[70:71], v[70:71], v[84:85] op_sel_hi:[1,0]
	s_nop 0
	v_cvt_pk_bf16_f32 v66, v70, v71
	v_cvt_pk_bf16_f32 v67, v72, v73
	v_cvt_pk_bf16_f32 v68, v68, v69
	v_cvt_pk_bf16_f32 v69, v74, v75
	global_store_dwordx4 v[82:83], v[66:69], off offset:256
	ds_read_b128 v[66:69], v147 offset:1024
	v_add_u32_e32 v70, 0x80, v148
	v_ashrrev_i32_e32 v71, 31, v70
	v_mul_lo_u32 v74, s68, v71
	v_mul_lo_u32 v75, s69, v70
	s_waitcnt lgkmcnt(0)
	v_mov_b32_e32 v72, v67
	v_mov_b32_e32 v73, v68
	v_mov_b32_e32 v67, v69
	v_pk_add_f32 v[66:67], v[72:73], v[66:67]
	v_mad_u64_u32 v[70:71], s[16:17], s68, v70, 0
	v_add_f32_e32 v66, v66, v67
	v_fmamk_f32 v66, v66, 0x3a800000, v155
	v_add3_u32 v71, v71, v74, v75
	v_rsq_f32_e32 v68, v66
	v_lshl_add_u64 v[66:67], v[70:71], 1, s[78:79]
	v_max_f32_e32 v71, 0, v65
	v_max_f32_e32 v70, 0, v64
	v_max_f32_e32 v73, 0, v63
	v_max_f32_e32 v72, 0, v62
	v_mul_f32_e32 v68, v68, v68
	v_pk_mul_f32 v[62:63], v[62:63], v[72:73]
	v_pk_mul_f32 v[64:65], v[64:65], v[70:71]
	v_pk_mul_f32 v[62:63], v[62:63], v[68:69] op_sel_hi:[1,0]
	v_pk_mul_f32 v[64:65], v[64:65], v[68:69] op_sel_hi:[1,0]
	v_max_f32_e32 v71, 0, v61
	v_max_f32_e32 v70, 0, v60
	v_max_f32_e32 v73, 0, v59
	v_max_f32_e32 v72, 0, v58
	v_pk_mul_f32 v[58:59], v[58:59], v[72:73]
	v_pk_mul_f32 v[60:61], v[60:61], v[70:71]
	v_lshl_add_u64 v[66:67], v[66:67], 0, v[140:141]
	v_pk_mul_f32 v[70:71], v[60:61], v[68:69] op_sel_hi:[1,0]
	v_pk_mul_f32 v[60:61], v[58:59], v[68:69] op_sel_hi:[1,0]
	v_cvt_pk_bf16_f32 v58, v62, v63
	v_cvt_pk_bf16_f32 v59, v64, v65
	s_nop 0
	v_cvt_pk_bf16_f32 v60, v60, v61
	v_cvt_pk_bf16_f32 v61, v70, v71
	global_store_dwordx4 v[66:67], v[58:61], off
	s_nop 1
	v_max_f32_e32 v59, 0, v57
	v_max_f32_e32 v61, 0, v55
	v_max_f32_e32 v58, 0, v56
	v_max_f32_e32 v60, 0, v54
	v_pk_mul_f32 v[54:55], v[54:55], v[60:61]
	v_pk_mul_f32 v[56:57], v[56:57], v[58:59]
	v_max_f32_e32 v59, 0, v53
	v_max_f32_e32 v61, 0, v51
	v_max_f32_e32 v58, 0, v52
	v_max_f32_e32 v60, 0, v50
	v_pk_mul_f32 v[50:51], v[50:51], v[60:61]
	v_pk_mul_f32 v[52:53], v[52:53], v[58:59]
	v_pk_mul_f32 v[56:57], v[56:57], v[68:69] op_sel_hi:[1,0]
	v_pk_mul_f32 v[58:59], v[52:53], v[68:69] op_sel_hi:[1,0]
	v_pk_mul_f32 v[52:53], v[50:51], v[68:69] op_sel_hi:[1,0]
	v_pk_mul_f32 v[54:55], v[54:55], v[68:69] op_sel_hi:[1,0]
	s_nop 0
	v_cvt_pk_bf16_f32 v50, v54, v55
	v_cvt_pk_bf16_f32 v51, v56, v57
	v_cvt_pk_bf16_f32 v52, v52, v53
	v_cvt_pk_bf16_f32 v53, v58, v59
	global_store_dwordx4 v[66:67], v[50:53], off offset:256
	ds_read_b128 v[50:53], v147 offset:1280
	v_add_u32_e32 v54, 0x90, v148
	v_ashrrev_i32_e32 v55, 31, v54
	v_mul_lo_u32 v58, s68, v55
	v_mul_lo_u32 v59, s69, v54
	s_waitcnt lgkmcnt(0)
	v_mov_b32_e32 v56, v51
	v_mov_b32_e32 v57, v52
	v_mov_b32_e32 v51, v53
	v_pk_add_f32 v[50:51], v[56:57], v[50:51]
	v_mad_u64_u32 v[54:55], s[16:17], s68, v54, 0
	v_add_f32_e32 v50, v50, v51
	v_fmamk_f32 v50, v50, 0x3a800000, v155
	v_add3_u32 v55, v55, v58, v59
	v_rsq_f32_e32 v52, v50
	v_lshl_add_u64 v[50:51], v[54:55], 1, s[78:79]
	v_max_f32_e32 v55, 0, v49
	v_max_f32_e32 v54, 0, v48
	v_max_f32_e32 v57, 0, v47
	v_max_f32_e32 v56, 0, v46
	v_mul_f32_e32 v52, v52, v52
	v_pk_mul_f32 v[46:47], v[46:47], v[56:57]
	v_pk_mul_f32 v[48:49], v[48:49], v[54:55]
	v_pk_mul_f32 v[46:47], v[46:47], v[52:53] op_sel_hi:[1,0]
	v_pk_mul_f32 v[48:49], v[48:49], v[52:53] op_sel_hi:[1,0]
	v_max_f32_e32 v55, 0, v45
	v_max_f32_e32 v54, 0, v44
	v_max_f32_e32 v57, 0, v43
	v_max_f32_e32 v56, 0, v42
	v_pk_mul_f32 v[42:43], v[42:43], v[56:57]
	v_pk_mul_f32 v[44:45], v[44:45], v[54:55]
	v_lshl_add_u64 v[50:51], v[50:51], 0, v[140:141]
	v_pk_mul_f32 v[54:55], v[44:45], v[52:53] op_sel_hi:[1,0]
	v_pk_mul_f32 v[44:45], v[42:43], v[52:53] op_sel_hi:[1,0]
	v_cvt_pk_bf16_f32 v42, v46, v47
	v_cvt_pk_bf16_f32 v43, v48, v49
	s_nop 0
	v_cvt_pk_bf16_f32 v44, v44, v45
	v_cvt_pk_bf16_f32 v45, v54, v55
	global_store_dwordx4 v[50:51], v[42:45], off
	s_nop 1
	v_max_f32_e32 v43, 0, v41
	v_max_f32_e32 v45, 0, v39
	v_max_f32_e32 v42, 0, v40
	v_max_f32_e32 v44, 0, v38
	v_pk_mul_f32 v[38:39], v[38:39], v[44:45]
	v_pk_mul_f32 v[40:41], v[40:41], v[42:43]
	v_max_f32_e32 v43, 0, v37
	v_max_f32_e32 v45, 0, v35
	v_max_f32_e32 v42, 0, v36
	v_max_f32_e32 v44, 0, v34
	v_pk_mul_f32 v[34:35], v[34:35], v[44:45]
	v_pk_mul_f32 v[36:37], v[36:37], v[42:43]
	v_pk_mul_f32 v[40:41], v[40:41], v[52:53] op_sel_hi:[1,0]
	v_pk_mul_f32 v[42:43], v[36:37], v[52:53] op_sel_hi:[1,0]
	v_pk_mul_f32 v[36:37], v[34:35], v[52:53] op_sel_hi:[1,0]
	v_pk_mul_f32 v[38:39], v[38:39], v[52:53] op_sel_hi:[1,0]
	s_nop 0
	v_cvt_pk_bf16_f32 v34, v38, v39
	v_cvt_pk_bf16_f32 v35, v40, v41
	v_cvt_pk_bf16_f32 v36, v36, v37
	v_cvt_pk_bf16_f32 v37, v42, v43
	global_store_dwordx4 v[50:51], v[34:37], off offset:256
	ds_read_b128 v[34:37], v147 offset:1536
	v_add_u32_e32 v38, 0xa0, v148
	v_ashrrev_i32_e32 v39, 31, v38
	v_mul_lo_u32 v42, s68, v39
	v_mul_lo_u32 v43, s69, v38
	s_waitcnt lgkmcnt(0)
	v_mov_b32_e32 v40, v35
	v_mov_b32_e32 v41, v36
	v_mov_b32_e32 v35, v37
	v_pk_add_f32 v[34:35], v[40:41], v[34:35]
	v_mad_u64_u32 v[38:39], s[16:17], s68, v38, 0
	v_add_f32_e32 v34, v34, v35
	v_fmamk_f32 v34, v34, 0x3a800000, v155
	v_add3_u32 v39, v39, v42, v43
	v_rsq_f32_e32 v36, v34
	v_lshl_add_u64 v[34:35], v[38:39], 1, s[78:79]
	v_max_f32_e32 v39, 0, v33
	v_max_f32_e32 v38, 0, v32
	v_max_f32_e32 v41, 0, v31
	v_max_f32_e32 v40, 0, v30
	v_mul_f32_e32 v36, v36, v36
	v_pk_mul_f32 v[30:31], v[30:31], v[40:41]
	v_pk_mul_f32 v[32:33], v[32:33], v[38:39]
	v_pk_mul_f32 v[30:31], v[30:31], v[36:37] op_sel_hi:[1,0]
	v_pk_mul_f32 v[32:33], v[32:33], v[36:37] op_sel_hi:[1,0]
	v_max_f32_e32 v39, 0, v29
	v_max_f32_e32 v38, 0, v28
	v_max_f32_e32 v41, 0, v27
	v_max_f32_e32 v40, 0, v26
	v_pk_mul_f32 v[26:27], v[26:27], v[40:41]
	v_pk_mul_f32 v[28:29], v[28:29], v[38:39]
	v_lshl_add_u64 v[34:35], v[34:35], 0, v[140:141]
	v_pk_mul_f32 v[38:39], v[28:29], v[36:37] op_sel_hi:[1,0]
	v_pk_mul_f32 v[28:29], v[26:27], v[36:37] op_sel_hi:[1,0]
	v_cvt_pk_bf16_f32 v26, v30, v31
	v_cvt_pk_bf16_f32 v27, v32, v33
	s_nop 0
	v_cvt_pk_bf16_f32 v28, v28, v29
	v_cvt_pk_bf16_f32 v29, v38, v39
	global_store_dwordx4 v[34:35], v[26:29], off
	s_nop 1
	v_max_f32_e32 v27, 0, v25
	v_max_f32_e32 v29, 0, v23
	v_max_f32_e32 v26, 0, v24
	v_max_f32_e32 v28, 0, v22
	v_pk_mul_f32 v[22:23], v[22:23], v[28:29]
	v_pk_mul_f32 v[24:25], v[24:25], v[26:27]
	v_max_f32_e32 v27, 0, v21
	v_max_f32_e32 v29, 0, v19
	v_max_f32_e32 v26, 0, v20
	v_max_f32_e32 v28, 0, v18
	v_pk_mul_f32 v[18:19], v[18:19], v[28:29]
	v_pk_mul_f32 v[20:21], v[20:21], v[26:27]
	v_pk_mul_f32 v[24:25], v[24:25], v[36:37] op_sel_hi:[1,0]
	v_pk_mul_f32 v[26:27], v[20:21], v[36:37] op_sel_hi:[1,0]
	v_pk_mul_f32 v[20:21], v[18:19], v[36:37] op_sel_hi:[1,0]
	v_pk_mul_f32 v[22:23], v[22:23], v[36:37] op_sel_hi:[1,0]
	s_nop 0
	v_cvt_pk_bf16_f32 v18, v22, v23
	v_cvt_pk_bf16_f32 v19, v24, v25
	v_cvt_pk_bf16_f32 v20, v20, v21
	v_cvt_pk_bf16_f32 v21, v26, v27
	global_store_dwordx4 v[34:35], v[18:21], off offset:256
	ds_read_b128 v[18:21], v147 offset:1792
	v_add_u32_e32 v22, 0xb0, v148
	v_ashrrev_i32_e32 v23, 31, v22
	v_mul_lo_u32 v26, s68, v23
	v_mul_lo_u32 v27, s69, v22
	s_waitcnt lgkmcnt(0)
	v_mov_b32_e32 v24, v19
	v_mov_b32_e32 v25, v20
	v_mov_b32_e32 v19, v21
	v_pk_add_f32 v[18:19], v[24:25], v[18:19]
	v_mad_u64_u32 v[22:23], s[16:17], s68, v22, 0
	v_add_f32_e32 v18, v18, v19
	v_fmamk_f32 v18, v18, 0x3a800000, v155
	v_add3_u32 v23, v23, v26, v27
	v_rsq_f32_e32 v20, v18
	v_lshl_add_u64 v[18:19], v[22:23], 1, s[78:79]
	v_max_f32_e32 v23, 0, v17
	v_max_f32_e32 v22, 0, v16
	v_max_f32_e32 v25, 0, v15
	v_max_f32_e32 v24, 0, v14
	v_mul_f32_e32 v20, v20, v20
	v_pk_mul_f32 v[14:15], v[14:15], v[24:25]
	v_pk_mul_f32 v[16:17], v[16:17], v[22:23]
	v_pk_mul_f32 v[14:15], v[14:15], v[20:21] op_sel_hi:[1,0]
	v_pk_mul_f32 v[16:17], v[16:17], v[20:21] op_sel_hi:[1,0]
	v_max_f32_e32 v23, 0, v13
	v_max_f32_e32 v22, 0, v12
	v_max_f32_e32 v25, 0, v11
	v_max_f32_e32 v24, 0, v10
	v_pk_mul_f32 v[10:11], v[10:11], v[24:25]
	v_pk_mul_f32 v[12:13], v[12:13], v[22:23]
	v_lshl_add_u64 v[18:19], v[18:19], 0, v[140:141]
	v_pk_mul_f32 v[22:23], v[12:13], v[20:21] op_sel_hi:[1,0]
	v_pk_mul_f32 v[12:13], v[10:11], v[20:21] op_sel_hi:[1,0]
	v_cvt_pk_bf16_f32 v10, v14, v15
	v_cvt_pk_bf16_f32 v11, v16, v17
	s_nop 0
	v_cvt_pk_bf16_f32 v12, v12, v13
	v_cvt_pk_bf16_f32 v13, v22, v23
	global_store_dwordx4 v[18:19], v[10:13], off
	s_nop 1
	v_max_f32_e32 v11, 0, v9
	v_max_f32_e32 v13, 0, v7
	v_max_f32_e32 v10, 0, v8
	v_max_f32_e32 v12, 0, v6
	v_pk_mul_f32 v[6:7], v[6:7], v[12:13]
	v_pk_mul_f32 v[8:9], v[8:9], v[10:11]
	v_max_f32_e32 v11, 0, v5
	v_max_f32_e32 v13, 0, v3
	v_max_f32_e32 v10, 0, v4
	v_max_f32_e32 v12, 0, v2
	v_pk_mul_f32 v[2:3], v[2:3], v[12:13]
	v_pk_mul_f32 v[4:5], v[4:5], v[10:11]
	v_pk_mul_f32 v[8:9], v[8:9], v[20:21] op_sel_hi:[1,0]
	v_pk_mul_f32 v[10:11], v[4:5], v[20:21] op_sel_hi:[1,0]
	v_pk_mul_f32 v[4:5], v[2:3], v[20:21] op_sel_hi:[1,0]
	v_pk_mul_f32 v[6:7], v[6:7], v[20:21] op_sel_hi:[1,0]
	s_nop 0
	v_cvt_pk_bf16_f32 v2, v6, v7
	v_cvt_pk_bf16_f32 v3, v8, v9
	v_cvt_pk_bf16_f32 v4, v4, v5
	v_cvt_pk_bf16_f32 v5, v10, v11
	global_store_dwordx4 v[18:19], v[2:5], off offset:256
	s_cbranch_vccnz .LBB0_325
	s_nop 0
	v_lshl_add_u32 v2, s61, 8, v145
	v_ashrrev_i32_e32 v3, 31, v2
	s_mov_b32 m0, s18
	v_lshl_add_u64 v[2:3], v[2:3], 4, s[96:97]
	s_mov_b64 s[6:7], 0x800
	global_load_lds_dwordx4 v[2:3], off
	v_lshl_add_u64 v[2:3], v[2:3], 0, s[6:7]
	s_add_i32 m0, s18, 0x400
	s_andn2_b64 vcc, exec, s[8:9]
	global_load_lds_dwordx4 v[2:3], off
	s_cbranch_vccnz .LBB0_324
	s_barrier
	s_branch .LBB0_324
